# phases with only 16-byte stores (P5,P7,P8,P12,P14,P15) store write-through (sc1) and the barrier after them drops buffer_wbl2
# baseline (speedup 1.0000x reference)
.LBB0_640:
	v_mov_b32_e32 v138, v140
	v_mov_b32_e32 v139, v141
	s_lshl_b32 s45, s52, 8
	s_add_i32 s45, s45, s70
	v_add_u32_e32 v138, s45, v138
	s_lshl_b32 s45, s77, 8
	s_or_b32 s45, s45, s71
	v_lshl_add_u32 v146, v139, 3, s45
	v_ashrrev_i32_e32 v139, 31, v138
	v_lshlrev_b64 v[138:139], 11, v[138:139]
	v_ashrrev_i32_e32 v147, 31, v146
	v_lshl_add_u64 v[138:139], s[14:15], 0, v[138:139]
	v_lshl_add_u64 v[138:139], v[146:147], 1, v[138:139]
	s_mov_b32 s45, 0x8000
	v_cvt_pk_bf16_f32 v120, v120, v121
	v_cvt_pk_bf16_f32 v121, v122, v123
	v_cvt_pk_bf16_f32 v122, v112, v113
	v_cvt_pk_bf16_f32 v123, v114, v115
	global_store_dwordx4 v[138:139], v[120:123], off sc1
	v_cvt_pk_bf16_f32 v112, v124, v125
	v_cvt_pk_bf16_f32 v113, v126, v127
	v_cvt_pk_bf16_f32 v114, v116, v117
	v_cvt_pk_bf16_f32 v115, v118, v119
	global_store_dwordx4 v[138:139], v[112:115], off offset:256 sc1
	s_mov_b64 s[54:55], 0x8000
	v_cvt_pk_bf16_f32 v108, v108, v109
	v_cvt_pk_bf16_f32 v109, v110, v111
	v_cvt_pk_bf16_f32 v110, v104, v105
	v_add_co_u32_e32 v104, vcc, s45, v138
	v_lshl_add_u64 v[112:113], v[138:139], 0, s[54:55]
	s_nop 0
	v_addc_co_u32_e32 v105, vcc, 0, v139, vcc
	s_mov_b32 s45, 0x10000
	v_cvt_pk_bf16_f32 v111, v106, v107
	global_store_dwordx4 v[104:105], v[108:111], off sc1
	v_cvt_pk_bf16_f32 v100, v100, v101
	v_cvt_pk_bf16_f32 v101, v102, v103
	v_cvt_pk_bf16_f32 v102, v96, v97
	v_cvt_pk_bf16_f32 v103, v98, v99
	global_store_dwordx4 v[112:113], v[100:103], off offset:256 sc1
	s_mov_b64 s[54:55], 0x10000
	v_cvt_pk_bf16_f32 v92, v92, v93
	v_cvt_pk_bf16_f32 v93, v94, v95
	v_cvt_pk_bf16_f32 v94, v88, v89
	v_add_co_u32_e32 v88, vcc, s45, v138
	v_lshl_add_u64 v[96:97], v[138:139], 0, s[54:55]
	s_nop 0
	v_addc_co_u32_e32 v89, vcc, 0, v139, vcc
	s_mov_b32 s45, 0x18000
	v_cvt_pk_bf16_f32 v95, v90, v91
	global_store_dwordx4 v[88:89], v[92:95], off sc1
	v_cvt_pk_bf16_f32 v84, v84, v85
	v_cvt_pk_bf16_f32 v85, v86, v87
	v_cvt_pk_bf16_f32 v86, v80, v81
	v_cvt_pk_bf16_f32 v87, v82, v83
	global_store_dwordx4 v[96:97], v[84:87], off offset:256 sc1
	v_cvt_pk_bf16_f32 v60, v60, v61
	v_cvt_pk_bf16_f32 v61, v62, v63
	v_cvt_pk_bf16_f32 v62, v56, v57
	v_add_co_u32_e32 v56, vcc, s45, v138
	s_mov_b64 s[54:55], 0x18000
	s_nop 0
	v_addc_co_u32_e32 v57, vcc, 0, v139, vcc
	v_lshl_add_u64 v[80:81], v[138:139], 0, s[54:55]
	v_cvt_pk_bf16_f32 v63, v58, v59
	global_store_dwordx4 v[56:57], v[60:63], off sc1
	v_cvt_pk_bf16_f32 v52, v52, v53
	v_cvt_pk_bf16_f32 v53, v54, v55
	v_cvt_pk_bf16_f32 v54, v48, v49
	s_mov_b32 s45, 0x40000
	v_cvt_pk_bf16_f32 v55, v50, v51
	global_store_dwordx4 v[80:81], v[52:55], off offset:256 sc1
	v_cvt_pk_bf16_f32 v48, v76, v77
	v_cvt_pk_bf16_f32 v49, v78, v79
	v_cvt_pk_bf16_f32 v50, v72, v73
	v_cvt_pk_bf16_f32 v51, v74, v75
	s_mov_b64 s[54:55], 0x48000
	s_nop 0
	v_add_co_u32_e32 v54, vcc, s45, v138
	v_lshl_add_u64 v[52:53], v[138:139], 0, s[8:9]
	s_nop 0
	v_addc_co_u32_e32 v55, vcc, 0, v139, vcc
	global_store_dwordx4 v[54:55], v[48:51], off sc1
	s_nop 1
	v_cvt_pk_bf16_f32 v48, v68, v69
	v_cvt_pk_bf16_f32 v49, v70, v71
	v_cvt_pk_bf16_f32 v50, v64, v65
	v_cvt_pk_bf16_f32 v51, v66, v67
	global_store_dwordx4 v[52:53], v[48:51], off offset:256 sc1
	v_cvt_pk_bf16_f32 v44, v44, v45
	v_cvt_pk_bf16_f32 v45, v46, v47
	v_cvt_pk_bf16_f32 v46, v36, v37
	v_add_co_u32_e32 v36, vcc, s74, v138
	s_nop 0
	v_lshl_add_u64 v[48:49], v[138:139], 0, s[54:55]
	v_addc_co_u32_e32 v37, vcc, 0, v139, vcc
	v_cvt_pk_bf16_f32 v47, v38, v39
	global_store_dwordx4 v[36:37], v[44:47], off sc1
	v_cvt_pk_bf16_f32 v36, v40, v41
	v_cvt_pk_bf16_f32 v37, v42, v43
	v_cvt_pk_bf16_f32 v38, v32, v33
	v_cvt_pk_bf16_f32 v39, v34, v35
	global_store_dwordx4 v[48:49], v[36:39], off offset:256 sc1
	v_cvt_pk_bf16_f32 v28, v28, v29
	v_cvt_pk_bf16_f32 v29, v30, v31
	v_cvt_pk_bf16_f32 v30, v20, v21
	v_add_co_u32_e32 v20, vcc, s75, v138
	v_lshl_add_u64 v[32:33], v[138:139], 0, s[40:41]
	s_nop 0
	v_addc_co_u32_e32 v21, vcc, 0, v139, vcc
	v_cvt_pk_bf16_f32 v31, v22, v23
	global_store_dwordx4 v[20:21], v[28:31], off sc1
	v_cvt_pk_bf16_f32 v20, v24, v25
	v_cvt_pk_bf16_f32 v21, v26, v27
	v_cvt_pk_bf16_f32 v22, v16, v17
	v_cvt_pk_bf16_f32 v23, v18, v19
	global_store_dwordx4 v[32:33], v[20:23], off offset:256 sc1
	v_cvt_pk_bf16_f32 v12, v12, v13
	v_cvt_pk_bf16_f32 v13, v14, v15
	v_cvt_pk_bf16_f32 v14, v4, v5
	v_add_co_u32_e32 v4, vcc, s76, v138
	v_lshl_add_u64 v[16:17], v[138:139], 0, s[42:43]
	s_nop 0
	v_addc_co_u32_e32 v5, vcc, 0, v139, vcc
	s_andn2_b64 vcc, exec, s[4:5]
	s_mov_b64 s[4:5], -1
	v_cvt_pk_bf16_f32 v15, v6, v7
	global_store_dwordx4 v[4:5], v[12:15], off sc1
	v_cvt_pk_bf16_f32 v4, v8, v9
	v_cvt_pk_bf16_f32 v5, v10, v11
	v_cvt_pk_bf16_f32 v6, v0, v1
	v_cvt_pk_bf16_f32 v7, v2, v3
	global_store_dwordx4 v[16:17], v[4:7], off offset:256 sc1
	s_cbranch_vccnz .LBB0_629
	s_andn2_b64 vcc, exec, s[12:13]
	s_cbranch_vccnz .LBB0_628
	s_barrier
	s_branch .LBB0_628

.LBB0_677:
	s_andn2_saveexec_b64 s[14:15], s[14:15]
	s_cbranch_execz .LBB0_697
	s_mov_b64 s[14:15], exec
	s_waitcnt lgkmcnt(0)
	s_waitcnt vmcnt(0)
	v_mbcnt_lo_u32_b32 v1, s14, 0
	v_mbcnt_hi_u32_b32 v1, s15, v1
	v_cmp_eq_u32_e32 vcc, 0, v1
	s_and_saveexec_b64 s[16:17], vcc
	s_cbranch_execz .LBB0_680
	s_bcnt1_i32_b64 s3, s[14:15]
	v_mov_b32_e32 v2, 0x3000
	v_mov_b32_e32 v3, s3
	global_atomic_add v2, v2, v3, s[10:11] offset:1024 sc0

.LBB0_783:
	s_waitcnt vmcnt(0)
	v_mul_f32_e32 v158, 0xbfb8aa3b, v153
	v_pk_mul_f32 v[160:161], v[158:159], v[122:123] op_sel_hi:[0,1]
	v_pk_mul_f32 v[122:123], v[122:123], v[126:127]
	v_pk_mul_f32 v[126:127], v[158:159], v[112:113] op_sel_hi:[0,1]
	v_pk_mul_f32 v[162:163], v[158:159], v[120:121] op_sel_hi:[0,1]
	v_pk_mul_f32 v[120:121], v[120:121], v[124:125]
	v_pk_mul_f32 v[124:125], v[158:159], v[114:115] op_sel_hi:[0,1]
	v_exp_f32_e32 v126, v126
	v_exp_f32_e32 v127, v127
	v_exp_f32_e32 v162, v162
	v_exp_f32_e32 v163, v163
	v_exp_f32_e32 v160, v160
	v_exp_f32_e32 v161, v161
	v_exp_f32_e32 v124, v124
	v_exp_f32_e32 v125, v125
	v_mov_b32_e32 v138, v140
	v_mov_b32_e32 v139, v141
	v_pk_add_f32 v[126:127], v[126:127], 1.0 op_sel_hi:[1,0]
	v_pk_add_f32 v[160:161], v[160:161], 1.0 op_sel_hi:[1,0]
	v_add_u32_e32 v154, s45, v138
	s_lshl_b32 s45, s76, 7
	v_pk_add_f32 v[162:163], v[162:163], 1.0 op_sel_hi:[1,0]
	v_pk_add_f32 v[124:125], v[124:125], 1.0 op_sel_hi:[1,0]
	v_rcp_f32_e32 v126, v126
	v_rcp_f32_e32 v127, v127
	s_or_b32 s45, s45, s72
	v_rcp_f32_e32 v162, v162
	v_rcp_f32_e32 v163, v163
	v_rcp_f32_e32 v160, v160
	v_rcp_f32_e32 v161, v161
	v_rcp_f32_e32 v124, v124
	v_rcp_f32_e32 v125, v125
	v_lshl_add_u32 v156, v139, 3, s45
	v_mul_f32_e32 v166, v153, v153
	v_pk_mul_f32 v[112:113], v[112:113], v[116:117]
	v_ashrrev_i32_e32 v157, 31, v156
	v_mov_b64_e32 v[138:139], s[14:15]
	v_pk_mul_f32 v[114:115], v[114:115], v[118:119]
	v_pk_mul_f32 v[112:113], v[166:167], v[112:113] op_sel_hi:[0,1]
	v_mad_i64_i32 v[164:165], s[52:53], v154, s75, v[138:139]
	v_pk_mul_f32 v[120:121], v[166:167], v[120:121] op_sel_hi:[0,1]
	v_pk_mul_f32 v[122:123], v[166:167], v[122:123] op_sel_hi:[0,1]
	v_pk_mul_f32 v[114:115], v[166:167], v[114:115] op_sel_hi:[0,1]
	v_pk_mul_f32 v[116:117], v[126:127], v[112:113]
	v_lshlrev_b64 v[112:113], 1, v[156:157]
	v_pk_mul_f32 v[122:123], v[160:161], v[122:123]
	v_pk_mul_f32 v[120:121], v[162:163], v[120:121]
	v_pk_mul_f32 v[118:119], v[124:125], v[114:115]
	v_lshl_add_u64 v[124:125], v[164:165], 0, v[112:113]
	v_cvt_pk_bf16_f32 v114, v120, v121
	v_cvt_pk_bf16_f32 v115, v122, v123
	v_cvt_pk_bf16_f32 v116, v116, v117
	v_cvt_pk_bf16_f32 v117, v118, v119
	global_store_dwordx4 v[124:125], v[114:117], off sc1
	v_mul_f32_e32 v122, v152, v152
	s_andn2_b64 vcc, exec, s[4:5]
	v_add_u32_e32 v115, 16, v154
	v_mul_f32_e32 v114, 0xbfb8aa3b, v152
	v_pk_mul_f32 v[116:117], v[114:115], v[106:107] op_sel_hi:[0,1]
	v_pk_mul_f32 v[118:119], v[114:115], v[104:105] op_sel_hi:[0,1]
	v_pk_mul_f32 v[106:107], v[106:107], v[110:111]
	v_pk_mul_f32 v[104:105], v[104:105], v[108:109]
	v_pk_mul_f32 v[108:109], v[114:115], v[98:99] op_sel_hi:[0,1]
	v_pk_mul_f32 v[110:111], v[114:115], v[96:97] op_sel_hi:[0,1]
	v_exp_f32_e32 v118, v118
	v_exp_f32_e32 v119, v119
	v_exp_f32_e32 v116, v116
	v_exp_f32_e32 v117, v117
	v_exp_f32_e32 v110, v110
	v_exp_f32_e32 v108, v108
	v_exp_f32_e32 v109, v109
	v_exp_f32_e32 v111, v111
	v_pk_add_f32 v[116:117], v[116:117], 1.0 op_sel_hi:[1,0]
	v_pk_add_f32 v[118:119], v[118:119], 1.0 op_sel_hi:[1,0]
	v_pk_add_f32 v[108:109], v[108:109], 1.0 op_sel_hi:[1,0]
	v_pk_add_f32 v[110:111], v[110:111], 1.0 op_sel_hi:[1,0]
	v_rcp_f32_e32 v118, v118
	v_rcp_f32_e32 v119, v119
	v_rcp_f32_e32 v116, v116
	v_rcp_f32_e32 v117, v117
	v_rcp_f32_e32 v110, v110
	v_rcp_f32_e32 v111, v111
	v_rcp_f32_e32 v108, v108
	v_rcp_f32_e32 v109, v109
	v_pk_mul_f32 v[98:99], v[98:99], v[102:103]
	v_pk_mul_f32 v[96:97], v[96:97], v[100:101]
	v_mad_i64_i32 v[120:121], s[52:53], v115, s75, v[138:139]
	v_pk_mul_f32 v[104:105], v[122:123], v[104:105] op_sel_hi:[0,1]
	v_pk_mul_f32 v[106:107], v[122:123], v[106:107] op_sel_hi:[0,1]
	v_pk_mul_f32 v[96:97], v[122:123], v[96:97] op_sel_hi:[0,1]
	v_pk_mul_f32 v[98:99], v[122:123], v[98:99] op_sel_hi:[0,1]
	v_pk_mul_f32 v[106:107], v[116:117], v[106:107]
	v_pk_mul_f32 v[104:105], v[118:119], v[104:105]
	v_pk_mul_f32 v[100:101], v[108:109], v[98:99]
	v_pk_mul_f32 v[98:99], v[110:111], v[96:97]
	v_lshl_add_u64 v[102:103], v[120:121], 0, v[112:113]
	v_cvt_pk_bf16_f32 v96, v104, v105
	v_cvt_pk_bf16_f32 v97, v106, v107
	v_cvt_pk_bf16_f32 v98, v98, v99
	v_cvt_pk_bf16_f32 v99, v100, v101
	global_store_dwordx4 v[102:103], v[96:99], off sc1
	v_mul_f32_e32 v104, v151, v151
	s_mov_b64 s[4:5], -1
	v_add_u32_e32 v97, 32, v154
	v_mul_f32_e32 v96, 0xbfb8aa3b, v151
	v_pk_mul_f32 v[98:99], v[96:97], v[90:91] op_sel_hi:[0,1]
	v_pk_mul_f32 v[100:101], v[96:97], v[88:89] op_sel_hi:[0,1]
	v_pk_mul_f32 v[90:91], v[90:91], v[94:95]
	v_pk_mul_f32 v[88:89], v[88:89], v[92:93]
	v_pk_mul_f32 v[92:93], v[96:97], v[82:83] op_sel_hi:[0,1]
	v_pk_mul_f32 v[94:95], v[96:97], v[80:81] op_sel_hi:[0,1]
	v_exp_f32_e32 v100, v100
	v_exp_f32_e32 v101, v101
	v_exp_f32_e32 v98, v98
	v_exp_f32_e32 v99, v99
	v_exp_f32_e32 v94, v94
	v_exp_f32_e32 v92, v92
	v_exp_f32_e32 v93, v93
	v_exp_f32_e32 v95, v95
	v_pk_add_f32 v[98:99], v[98:99], 1.0 op_sel_hi:[1,0]
	v_pk_add_f32 v[100:101], v[100:101], 1.0 op_sel_hi:[1,0]
	v_pk_add_f32 v[92:93], v[92:93], 1.0 op_sel_hi:[1,0]
	v_pk_add_f32 v[94:95], v[94:95], 1.0 op_sel_hi:[1,0]
	v_rcp_f32_e32 v100, v100
	v_rcp_f32_e32 v101, v101
	v_rcp_f32_e32 v98, v98
	v_rcp_f32_e32 v99, v99
	v_rcp_f32_e32 v94, v94
	v_rcp_f32_e32 v95, v95
	v_rcp_f32_e32 v92, v92
	v_rcp_f32_e32 v93, v93
	v_pk_mul_f32 v[82:83], v[82:83], v[86:87]
	v_pk_mul_f32 v[80:81], v[80:81], v[84:85]
	v_mad_i64_i32 v[102:103], s[52:53], v97, s75, v[138:139]
	v_pk_mul_f32 v[88:89], v[104:105], v[88:89] op_sel_hi:[0,1]
	v_pk_mul_f32 v[90:91], v[104:105], v[90:91] op_sel_hi:[0,1]
	v_pk_mul_f32 v[80:81], v[104:105], v[80:81] op_sel_hi:[0,1]
	v_pk_mul_f32 v[82:83], v[104:105], v[82:83] op_sel_hi:[0,1]
	v_pk_mul_f32 v[90:91], v[98:99], v[90:91]
	v_pk_mul_f32 v[88:89], v[100:101], v[88:89]
	v_pk_mul_f32 v[84:85], v[92:93], v[82:83]
	v_pk_mul_f32 v[82:83], v[94:95], v[80:81]
	v_lshl_add_u64 v[86:87], v[102:103], 0, v[112:113]
	v_cvt_pk_bf16_f32 v80, v88, v89
	v_cvt_pk_bf16_f32 v81, v90, v91
	v_cvt_pk_bf16_f32 v82, v82, v83
	v_cvt_pk_bf16_f32 v83, v84, v85
	global_store_dwordx4 v[86:87], v[80:83], off sc1
	v_mul_f32_e32 v88, v150, v150
	s_nop 0
	v_add_u32_e32 v81, 48, v154
	v_mul_f32_e32 v80, 0xbfb8aa3b, v150
	v_pk_mul_f32 v[82:83], v[80:81], v[74:75] op_sel_hi:[0,1]
	v_pk_mul_f32 v[84:85], v[80:81], v[72:73] op_sel_hi:[0,1]
	v_pk_mul_f32 v[74:75], v[74:75], v[78:79]
	v_pk_mul_f32 v[72:73], v[72:73], v[76:77]
	v_pk_mul_f32 v[76:77], v[80:81], v[58:59] op_sel_hi:[0,1]
	v_pk_mul_f32 v[78:79], v[80:81], v[56:57] op_sel_hi:[0,1]
	v_exp_f32_e32 v84, v84
	v_exp_f32_e32 v85, v85
	v_exp_f32_e32 v82, v82
	v_exp_f32_e32 v83, v83
	v_exp_f32_e32 v78, v78
	v_exp_f32_e32 v76, v76
	v_exp_f32_e32 v77, v77
	v_exp_f32_e32 v79, v79
	v_pk_add_f32 v[82:83], v[82:83], 1.0 op_sel_hi:[1,0]
	v_pk_add_f32 v[84:85], v[84:85], 1.0 op_sel_hi:[1,0]
	v_pk_add_f32 v[76:77], v[76:77], 1.0 op_sel_hi:[1,0]
	v_pk_add_f32 v[78:79], v[78:79], 1.0 op_sel_hi:[1,0]
	v_rcp_f32_e32 v84, v84
	v_rcp_f32_e32 v85, v85
	v_rcp_f32_e32 v82, v82
	v_rcp_f32_e32 v83, v83
	v_rcp_f32_e32 v78, v78
	v_rcp_f32_e32 v79, v79
	v_rcp_f32_e32 v76, v76
	v_rcp_f32_e32 v77, v77
	v_pk_mul_f32 v[58:59], v[58:59], v[66:67]
	v_pk_mul_f32 v[56:57], v[56:57], v[64:65]
	v_mad_i64_i32 v[86:87], s[52:53], v81, s75, v[138:139]
	v_pk_mul_f32 v[72:73], v[88:89], v[72:73] op_sel_hi:[0,1]
	v_pk_mul_f32 v[74:75], v[88:89], v[74:75] op_sel_hi:[0,1]
	v_pk_mul_f32 v[56:57], v[88:89], v[56:57] op_sel_hi:[0,1]
	v_pk_mul_f32 v[58:59], v[88:89], v[58:59] op_sel_hi:[0,1]
	v_pk_mul_f32 v[74:75], v[82:83], v[74:75]
	v_pk_mul_f32 v[72:73], v[84:85], v[72:73]
	v_pk_mul_f32 v[64:65], v[76:77], v[58:59]
	v_pk_mul_f32 v[58:59], v[78:79], v[56:57]
	v_lshl_add_u64 v[66:67], v[86:87], 0, v[112:113]
	v_cvt_pk_bf16_f32 v56, v72, v73
	v_cvt_pk_bf16_f32 v57, v74, v75
	v_cvt_pk_bf16_f32 v58, v58, v59
	v_cvt_pk_bf16_f32 v59, v64, v65
	global_store_dwordx4 v[66:67], v[56:59], off sc1
	v_mul_f32_e32 v72, v149, v149
	s_nop 0
	v_add_u32_e32 v57, 0x80, v154
	v_mul_f32_e32 v56, 0xbfb8aa3b, v149
	v_pk_mul_f32 v[58:59], v[56:57], v[62:63] op_sel_hi:[0,1]
	v_exp_f32_e32 v58, v58
	v_exp_f32_e32 v59, v59
	v_pk_mul_f32 v[64:65], v[56:57], v[60:61] op_sel_hi:[0,1]
	v_mad_i64_i32 v[66:67], s[52:53], v57, s75, v[138:139]
	v_pk_add_f32 v[58:59], v[58:59], 1.0 op_sel_hi:[1,0]
	v_pk_mul_f32 v[60:61], v[60:61], v[68:69]
	v_pk_mul_f32 v[68:69], v[56:57], v[50:51] op_sel_hi:[0,1]
	v_pk_mul_f32 v[56:57], v[56:57], v[48:49] op_sel_hi:[0,1]
	v_exp_f32_e32 v64, v64
	v_exp_f32_e32 v65, v65
	v_rcp_f32_e32 v58, v58
	v_rcp_f32_e32 v59, v59
	v_exp_f32_e32 v56, v56
	v_exp_f32_e32 v68, v68
	v_exp_f32_e32 v69, v69
	v_exp_f32_e32 v57, v57
	v_pk_mul_f32 v[62:63], v[62:63], v[70:71]
	v_pk_add_f32 v[64:65], v[64:65], 1.0 op_sel_hi:[1,0]
	v_pk_mul_f32 v[62:63], v[72:73], v[62:63] op_sel_hi:[0,1]
	v_pk_mul_f32 v[58:59], v[58:59], v[62:63]
	v_pk_add_f32 v[62:63], v[68:69], 1.0 op_sel_hi:[1,0]
	v_pk_add_f32 v[56:57], v[56:57], 1.0 op_sel_hi:[1,0]
	v_rcp_f32_e32 v64, v64
	v_rcp_f32_e32 v65, v65
	v_rcp_f32_e32 v56, v56
	v_rcp_f32_e32 v57, v57
	v_rcp_f32_e32 v62, v62
	v_rcp_f32_e32 v63, v63
	v_pk_mul_f32 v[50:51], v[50:51], v[54:55]
	v_pk_mul_f32 v[48:49], v[48:49], v[52:53]
	v_pk_mul_f32 v[60:61], v[72:73], v[60:61] op_sel_hi:[0,1]
	v_pk_mul_f32 v[48:49], v[72:73], v[48:49] op_sel_hi:[0,1]
	v_pk_mul_f32 v[50:51], v[72:73], v[50:51] op_sel_hi:[0,1]
	v_pk_mul_f32 v[60:61], v[64:65], v[60:61]
	v_pk_mul_f32 v[52:53], v[62:63], v[50:51]
	v_pk_mul_f32 v[50:51], v[56:57], v[48:49]
	v_lshl_add_u64 v[54:55], v[66:67], 0, v[112:113]
	v_cvt_pk_bf16_f32 v48, v60, v61
	v_cvt_pk_bf16_f32 v49, v58, v59
	v_cvt_pk_bf16_f32 v50, v50, v51
	v_cvt_pk_bf16_f32 v51, v52, v53
	global_store_dwordx4 v[54:55], v[48:51], off sc1
	v_mul_f32_e32 v56, v148, v148
	s_nop 0
	v_add_u32_e32 v49, 0x90, v154
	v_mul_f32_e32 v48, 0xbfb8aa3b, v148
	v_pk_mul_f32 v[50:51], v[48:49], v[42:43] op_sel_hi:[0,1]
	v_pk_mul_f32 v[52:53], v[48:49], v[40:41] op_sel_hi:[0,1]
	v_pk_mul_f32 v[42:43], v[42:43], v[46:47]
	v_pk_mul_f32 v[40:41], v[40:41], v[44:45]
	v_pk_mul_f32 v[44:45], v[48:49], v[34:35] op_sel_hi:[0,1]
	v_pk_mul_f32 v[46:47], v[48:49], v[32:33] op_sel_hi:[0,1]
	v_exp_f32_e32 v52, v52
	v_exp_f32_e32 v53, v53
	v_exp_f32_e32 v50, v50
	v_exp_f32_e32 v51, v51
	v_exp_f32_e32 v46, v46
	v_exp_f32_e32 v44, v44
	v_exp_f32_e32 v45, v45
	v_exp_f32_e32 v47, v47
	v_pk_add_f32 v[50:51], v[50:51], 1.0 op_sel_hi:[1,0]
	v_pk_add_f32 v[52:53], v[52:53], 1.0 op_sel_hi:[1,0]
	v_pk_add_f32 v[44:45], v[44:45], 1.0 op_sel_hi:[1,0]
	v_pk_add_f32 v[46:47], v[46:47], 1.0 op_sel_hi:[1,0]
	v_rcp_f32_e32 v52, v52
	v_rcp_f32_e32 v53, v53
	v_rcp_f32_e32 v50, v50
	v_rcp_f32_e32 v51, v51
	v_rcp_f32_e32 v46, v46
	v_rcp_f32_e32 v47, v47
	v_rcp_f32_e32 v44, v44
	v_rcp_f32_e32 v45, v45
	v_pk_mul_f32 v[34:35], v[34:35], v[38:39]
	v_pk_mul_f32 v[32:33], v[32:33], v[36:37]
	v_mad_i64_i32 v[54:55], s[52:53], v49, s75, v[138:139]
	v_pk_mul_f32 v[40:41], v[56:57], v[40:41] op_sel_hi:[0,1]
	v_pk_mul_f32 v[42:43], v[56:57], v[42:43] op_sel_hi:[0,1]
	v_pk_mul_f32 v[32:33], v[56:57], v[32:33] op_sel_hi:[0,1]
	v_pk_mul_f32 v[34:35], v[56:57], v[34:35] op_sel_hi:[0,1]
	v_pk_mul_f32 v[42:43], v[50:51], v[42:43]
	v_pk_mul_f32 v[40:41], v[52:53], v[40:41]
	v_pk_mul_f32 v[36:37], v[44:45], v[34:35]
	v_pk_mul_f32 v[34:35], v[46:47], v[32:33]
	v_lshl_add_u64 v[38:39], v[54:55], 0, v[112:113]
	v_cvt_pk_bf16_f32 v32, v40, v41
	v_cvt_pk_bf16_f32 v33, v42, v43
	v_cvt_pk_bf16_f32 v34, v34, v35
	v_cvt_pk_bf16_f32 v35, v36, v37
	global_store_dwordx4 v[38:39], v[32:35], off sc1
	v_mul_f32_e32 v40, v147, v147
	s_nop 0
	v_add_u32_e32 v33, 0xa0, v154
	v_mul_f32_e32 v32, 0xbfb8aa3b, v147
	v_pk_mul_f32 v[34:35], v[32:33], v[26:27] op_sel_hi:[0,1]
	v_pk_mul_f32 v[36:37], v[32:33], v[24:25] op_sel_hi:[0,1]
	v_pk_mul_f32 v[26:27], v[26:27], v[30:31]
	v_pk_mul_f32 v[24:25], v[24:25], v[28:29]
	v_pk_mul_f32 v[28:29], v[32:33], v[18:19] op_sel_hi:[0,1]
	v_pk_mul_f32 v[30:31], v[32:33], v[16:17] op_sel_hi:[0,1]
	v_exp_f32_e32 v36, v36
	v_exp_f32_e32 v37, v37
	v_exp_f32_e32 v34, v34
	v_exp_f32_e32 v35, v35
	v_exp_f32_e32 v30, v30
	v_exp_f32_e32 v28, v28
	v_exp_f32_e32 v29, v29
	v_exp_f32_e32 v31, v31
	v_pk_add_f32 v[34:35], v[34:35], 1.0 op_sel_hi:[1,0]
	v_pk_add_f32 v[36:37], v[36:37], 1.0 op_sel_hi:[1,0]
	v_pk_add_f32 v[28:29], v[28:29], 1.0 op_sel_hi:[1,0]
	v_pk_add_f32 v[30:31], v[30:31], 1.0 op_sel_hi:[1,0]
	v_rcp_f32_e32 v36, v36
	v_rcp_f32_e32 v37, v37
	v_rcp_f32_e32 v34, v34
	v_rcp_f32_e32 v35, v35
	v_rcp_f32_e32 v30, v30
	v_rcp_f32_e32 v31, v31
	v_rcp_f32_e32 v28, v28
	v_rcp_f32_e32 v29, v29
	v_pk_mul_f32 v[18:19], v[18:19], v[22:23]
	v_pk_mul_f32 v[16:17], v[16:17], v[20:21]
	v_mad_i64_i32 v[38:39], s[52:53], v33, s75, v[138:139]
	v_pk_mul_f32 v[24:25], v[40:41], v[24:25] op_sel_hi:[0,1]
	v_pk_mul_f32 v[26:27], v[40:41], v[26:27] op_sel_hi:[0,1]
	v_pk_mul_f32 v[16:17], v[40:41], v[16:17] op_sel_hi:[0,1]
	v_pk_mul_f32 v[18:19], v[40:41], v[18:19] op_sel_hi:[0,1]
	v_pk_mul_f32 v[26:27], v[34:35], v[26:27]
	v_pk_mul_f32 v[24:25], v[36:37], v[24:25]
	v_pk_mul_f32 v[20:21], v[28:29], v[18:19]
	v_pk_mul_f32 v[18:19], v[30:31], v[16:17]
	v_lshl_add_u64 v[22:23], v[38:39], 0, v[112:113]
	v_cvt_pk_bf16_f32 v16, v24, v25
	v_cvt_pk_bf16_f32 v17, v26, v27
	v_cvt_pk_bf16_f32 v18, v18, v19
	v_cvt_pk_bf16_f32 v19, v20, v21
	global_store_dwordx4 v[22:23], v[16:19], off sc1
	v_mul_f32_e32 v24, v146, v146
	s_nop 0
	v_add_u32_e32 v17, 0xb0, v154
	v_mul_f32_e32 v16, 0xbfb8aa3b, v146
	v_pk_mul_f32 v[18:19], v[16:17], v[10:11] op_sel_hi:[0,1]
	v_pk_mul_f32 v[20:21], v[16:17], v[8:9] op_sel_hi:[0,1]
	v_pk_mul_f32 v[10:11], v[10:11], v[14:15]
	v_pk_mul_f32 v[8:9], v[8:9], v[12:13]
	v_pk_mul_f32 v[12:13], v[16:17], v[2:3] op_sel_hi:[0,1]
	v_pk_mul_f32 v[14:15], v[16:17], v[0:1] op_sel_hi:[0,1]
	v_exp_f32_e32 v14, v14
	v_exp_f32_e32 v12, v12
	v_exp_f32_e32 v13, v13
	v_exp_f32_e32 v15, v15
	v_exp_f32_e32 v20, v20
	v_exp_f32_e32 v21, v21
	v_exp_f32_e32 v18, v18
	v_exp_f32_e32 v19, v19
	v_pk_add_f32 v[12:13], v[12:13], 1.0 op_sel_hi:[1,0]
	v_pk_add_f32 v[14:15], v[14:15], 1.0 op_sel_hi:[1,0]
	v_pk_add_f32 v[20:21], v[20:21], 1.0 op_sel_hi:[1,0]
	v_pk_add_f32 v[18:19], v[18:19], 1.0 op_sel_hi:[1,0]
	v_rcp_f32_e32 v14, v14
	v_rcp_f32_e32 v15, v15
	v_rcp_f32_e32 v12, v12
	v_rcp_f32_e32 v13, v13
	v_rcp_f32_e32 v20, v20
	v_rcp_f32_e32 v21, v21
	v_rcp_f32_e32 v18, v18
	v_rcp_f32_e32 v19, v19
	v_pk_mul_f32 v[2:3], v[2:3], v[6:7]
	v_pk_mul_f32 v[0:1], v[0:1], v[4:5]
	v_mad_i64_i32 v[22:23], s[52:53], v17, s75, v[138:139]
	v_pk_mul_f32 v[0:1], v[24:25], v[0:1] op_sel_hi:[0,1]
	v_pk_mul_f32 v[2:3], v[24:25], v[2:3] op_sel_hi:[0,1]
	v_pk_mul_f32 v[8:9], v[24:25], v[8:9] op_sel_hi:[0,1]
	v_pk_mul_f32 v[10:11], v[24:25], v[10:11] op_sel_hi:[0,1]
	v_pk_mul_f32 v[4:5], v[12:13], v[2:3]
	v_pk_mul_f32 v[2:3], v[14:15], v[0:1]
	v_lshl_add_u64 v[6:7], v[22:23], 0, v[112:113]
	v_pk_mul_f32 v[10:11], v[18:19], v[10:11]
	v_pk_mul_f32 v[8:9], v[20:21], v[8:9]
	s_nop 0
	v_cvt_pk_bf16_f32 v0, v8, v9
	v_cvt_pk_bf16_f32 v1, v10, v11
	v_cvt_pk_bf16_f32 v2, v2, v3
	v_cvt_pk_bf16_f32 v3, v4, v5
	global_store_dwordx4 v[6:7], v[0:3], off sc1
	s_cbranch_vccnz .LBB0_776
	s_andn2_b64 vcc, exec, s[12:13]
	s_cbranch_vccnz .LBB0_775
	s_barrier
	s_branch .LBB0_775

.LBB0_862:
	v_mov_b32_e32 v138, v140
	v_mov_b32_e32 v139, v141
	s_lshl_b32 s50, s77, 8
	s_add_i32 s50, s50, s67
	v_add_u32_e32 v138, s50, v138
	s_lshl_b32 s50, s78, 8
	s_or_b32 s50, s50, s68
	v_lshl_add_u32 v146, v139, 3, s50
	v_ashrrev_i32_e32 v139, 31, v138
	v_lshlrev_b64 v[138:139], 11, v[138:139]
	v_ashrrev_i32_e32 v147, 31, v146
	v_lshl_add_u64 v[138:139], s[16:17], 0, v[138:139]
	v_lshl_add_u64 v[138:139], v[146:147], 1, v[138:139]
	v_cvt_pk_bf16_f32 v120, v120, v121
	v_cvt_pk_bf16_f32 v121, v122, v123
	v_cvt_pk_bf16_f32 v122, v112, v113
	v_cvt_pk_bf16_f32 v123, v114, v115
	global_store_dwordx4 v[138:139], v[120:123], off sc1
	v_cvt_pk_bf16_f32 v112, v124, v125
	v_cvt_pk_bf16_f32 v113, v126, v127
	s_mov_b64 s[50:51], 0x8000
	v_cvt_pk_bf16_f32 v114, v116, v117
	v_cvt_pk_bf16_f32 v115, v118, v119
	global_store_dwordx4 v[138:139], v[112:115], off offset:256 sc1
	v_cvt_pk_bf16_f32 v108, v108, v109
	v_cvt_pk_bf16_f32 v109, v110, v111
	v_cvt_pk_bf16_f32 v110, v104, v105
	v_cvt_pk_bf16_f32 v111, v106, v107
	s_nop 1
	v_lshl_add_u64 v[112:113], v[138:139], 0, s[50:51]
	s_mov_b32 s50, 0x8000
	v_add_co_u32_e32 v104, vcc, s50, v138
	s_mov_b64 s[50:51], 0x10000
	s_nop 0
	v_addc_co_u32_e32 v105, vcc, 0, v139, vcc
	global_store_dwordx4 v[104:105], v[108:111], off sc1
	v_cvt_pk_bf16_f32 v100, v100, v101
	v_cvt_pk_bf16_f32 v101, v102, v103
	v_cvt_pk_bf16_f32 v102, v96, v97
	v_lshl_add_u64 v[96:97], v[138:139], 0, s[50:51]
	s_mov_b32 s50, 0x10000
	v_cvt_pk_bf16_f32 v103, v98, v99
	global_store_dwordx4 v[112:113], v[100:103], off offset:256 sc1
	v_cvt_pk_bf16_f32 v92, v92, v93
	v_cvt_pk_bf16_f32 v93, v94, v95
	v_cvt_pk_bf16_f32 v94, v88, v89
	v_add_co_u32_e32 v88, vcc, s50, v138
	s_mov_b64 s[50:51], 0x18000
	s_nop 0
	v_addc_co_u32_e32 v89, vcc, 0, v139, vcc
	v_cvt_pk_bf16_f32 v95, v90, v91
	global_store_dwordx4 v[88:89], v[92:95], off sc1
	v_cvt_pk_bf16_f32 v84, v84, v85
	v_cvt_pk_bf16_f32 v85, v86, v87
	v_cvt_pk_bf16_f32 v86, v80, v81
	v_lshl_add_u64 v[80:81], v[138:139], 0, s[50:51]
	s_mov_b32 s50, 0x18000
	v_cvt_pk_bf16_f32 v87, v82, v83
	global_store_dwordx4 v[96:97], v[84:87], off offset:256 sc1
	v_cvt_pk_bf16_f32 v60, v60, v61
	v_cvt_pk_bf16_f32 v61, v62, v63
	v_cvt_pk_bf16_f32 v62, v56, v57
	v_add_co_u32_e32 v56, vcc, s50, v138
	v_cvt_pk_bf16_f32 v63, v58, v59
	s_nop 1
	v_addc_co_u32_e32 v57, vcc, 0, v139, vcc
	global_store_dwordx4 v[56:57], v[60:63], off sc1
	v_cvt_pk_bf16_f32 v52, v52, v53
	v_cvt_pk_bf16_f32 v53, v54, v55
	v_cvt_pk_bf16_f32 v54, v48, v49
	v_cvt_pk_bf16_f32 v55, v50, v51
	global_store_dwordx4 v[80:81], v[52:55], off offset:256 sc1
	v_cvt_pk_bf16_f32 v48, v76, v77
	v_cvt_pk_bf16_f32 v49, v78, v79
	v_cvt_pk_bf16_f32 v50, v68, v69
	v_cvt_pk_bf16_f32 v51, v70, v71
	s_nop 1
	v_add_co_u32_e32 v54, vcc, s71, v138
	v_lshl_add_u64 v[52:53], v[138:139], 0, s[42:43]
	s_nop 0
	v_addc_co_u32_e32 v55, vcc, 0, v139, vcc
	global_store_dwordx4 v[54:55], v[48:51], off sc1
	s_nop 1
	v_cvt_pk_bf16_f32 v48, v72, v73
	v_cvt_pk_bf16_f32 v49, v74, v75
	v_cvt_pk_bf16_f32 v50, v64, v65
	v_cvt_pk_bf16_f32 v51, v66, v67
	global_store_dwordx4 v[52:53], v[48:51], off offset:256 sc1
	v_cvt_pk_bf16_f32 v44, v44, v45
	v_cvt_pk_bf16_f32 v45, v46, v47
	v_cvt_pk_bf16_f32 v46, v36, v37
	v_add_co_u32_e32 v36, vcc, s72, v138
	s_nop 0
	v_lshl_add_u64 v[48:49], v[138:139], 0, s[44:45]
	v_addc_co_u32_e32 v37, vcc, 0, v139, vcc
	v_cvt_pk_bf16_f32 v47, v38, v39
	global_store_dwordx4 v[36:37], v[44:47], off sc1
	v_cvt_pk_bf16_f32 v36, v40, v41
	v_cvt_pk_bf16_f32 v37, v42, v43
	v_cvt_pk_bf16_f32 v38, v32, v33
	v_cvt_pk_bf16_f32 v39, v34, v35
	global_store_dwordx4 v[48:49], v[36:39], off offset:256 sc1
	v_cvt_pk_bf16_f32 v28, v28, v29
	v_cvt_pk_bf16_f32 v29, v30, v31
	v_cvt_pk_bf16_f32 v30, v20, v21
	v_add_co_u32_e32 v20, vcc, s73, v138
	v_lshl_add_u64 v[32:33], v[138:139], 0, s[46:47]
	s_nop 0
	v_addc_co_u32_e32 v21, vcc, 0, v139, vcc
	v_cvt_pk_bf16_f32 v31, v22, v23
	global_store_dwordx4 v[20:21], v[28:31], off sc1
	v_cvt_pk_bf16_f32 v20, v24, v25
	v_cvt_pk_bf16_f32 v21, v26, v27
	v_cvt_pk_bf16_f32 v22, v16, v17
	v_cvt_pk_bf16_f32 v23, v18, v19
	global_store_dwordx4 v[32:33], v[20:23], off offset:256 sc1
	v_cvt_pk_bf16_f32 v12, v12, v13
	v_cvt_pk_bf16_f32 v13, v14, v15
	v_cvt_pk_bf16_f32 v14, v4, v5
	v_add_co_u32_e32 v4, vcc, s74, v138
	v_lshl_add_u64 v[16:17], v[138:139], 0, s[8:9]
	s_nop 0
	v_addc_co_u32_e32 v5, vcc, 0, v139, vcc
	s_and_b64 vcc, exec, s[4:5]
	s_mov_b64 s[4:5], -1
	v_cvt_pk_bf16_f32 v15, v6, v7
	global_store_dwordx4 v[4:5], v[12:15], off sc1
	v_cvt_pk_bf16_f32 v4, v8, v9
	v_cvt_pk_bf16_f32 v5, v10, v11
	v_cvt_pk_bf16_f32 v6, v0, v1
	v_cvt_pk_bf16_f32 v7, v2, v3
	global_store_dwordx4 v[16:17], v[4:7], off offset:256 sc1
	s_cbranch_vccnz .LBB0_847
	s_andn2_b64 vcc, exec, s[14:15]
	s_cbranch_vccnz .LBB0_846
	s_barrier
	s_branch .LBB0_846
